# attention logits per 32-key tile via bf16 MFMA (K tile x Q^T, f32 acc) through a per-wave LDS image instead of v_dot2c per key; S5 chain at raised wave priority; q loads and dt loads de-serialised
# speedup vs baseline: 1.0795x; 1.0191x over previous
; __device__ __forceinline__ void ssd_item(CPar p, int l, int item, float* sm) {
;     ...
;     { const int wv = tid >> 6, ln = tid & 63; float xv[5];
; #pragma unroll
;         for (int r = 0; r < 5; ++r) { const int c = wv + 8 * r, t = c * 64 + ln; xv[r] = (c < nch && t < T) ? DT[(size_t)row_of(s, t) * 16 + h] + dtb : -1e30f; }
; #pragma unroll
;         for (int r = 0; r < 5; ++r) { const int c = wv + 8 * r;
;             if (c < nch) { const float x = xv[r]; const float dtv = x < -1e29f ? 0.f : (x > 20.f ? x : log1pf(__expf(x))); float cs = dtv * aneg;
.LBB0_279:
	s_and_b64 s[12:13], s[40:41], exec
	s_cselect_b32 s12, 0x810, 64
	s_add_i32 s6, s12, 63
	s_lshl_b32 s16, s15, 6
	s_lshl_b32 s76, s15, 11
	s_lshl_b32 s21, s15, 4
	s_lshr_b32 s13, s6, 6
	s_add_i32 s16, s16, 0xf800
	s_add_i32 s20, s76, -16
	s_add_i32 s21, s21, 0x10400
	s_lshl_b32 s6, s1, 2
	s_waitcnt lgkmcnt(0)
	s_add_u32 s6, s94, s6
	s_addc_u32 s7, s95, 0
	s_add_u32 s28, s6, 0x3ddc1000
	v_cmp_gt_i32_e64 s[50:51], s13, v13
	v_cmp_gt_i32_e32 vcc, s12, v48
	s_addc_u32 s29, s7, 0
	s_and_b64 s[36:37], s[50:51], vcc
	v_mov_b32_e32 v20, 0xf149f2ca
	v_mov_b32_e32 v21, 0xf149f2ca
	v_mov_b32_e32 v190, 0xf149f2ca
	v_mov_b32_e32 v191, 0xf149f2ca
	v_mov_b32_e32 v192, 0xf149f2ca
	v_mov_b32_e32 v193, 0xf149f2ca
	v_mov_b32_e32 v194, 0xf149f2ca
	s_waitcnt vmcnt(0)
	v_cvt_pk_bf16_f32 v2, v11, v11
	ds_write_b16 v1, v2 offset:46544
	s_and_saveexec_b64 s[30:31], s[36:37]
	s_cbranch_execz .LBB0_281
	v_mov_b32_e32 v1, s20
	v_mov_b32_e32 v2, s21
	v_cmp_gt_i32_e32 vcc, 16, v48
	s_nop 1
	v_cndmask_b32_e32 v1, v1, v2, vcc
	v_mov_b32_e32 v2, s16
	v_cndmask_b32_e64 v1, v2, v1, s[40:41]
	v_add_u32_e32 v2, v1, v48
	v_ashrrev_i32_e32 v3, 31, v2
	v_lshlrev_b64 v[2:3], 6, v[2:3]
	v_lshl_add_u64 v[2:3], s[28:29], 0, v[2:3]
	global_load_dword v190, v[2:3], off
.LBB0_281:
	s_or_b64 exec, exec, s[30:31]
	v_and_b32_e32 v1, 63, v48
	v_add_u32_e32 v2, 8, v13
	v_lshl_or_b32 v18, v2, 6, v1
	v_cmp_gt_i32_e64 s[48:49], s13, v2
	v_cmp_gt_i32_e32 vcc, s12, v18
	s_and_b64 s[36:37], s[48:49], vcc
	s_and_saveexec_b64 s[30:31], s[36:37]
	s_cbranch_execz .LBB0_283
	v_mov_b32_e32 v2, s20
	v_mov_b32_e32 v3, s21
	v_cmp_gt_i32_e32 vcc, 16, v18
	s_nop 1
	v_cndmask_b32_e32 v2, v2, v3, vcc
	v_mov_b32_e32 v3, s16
	v_cndmask_b32_e64 v2, v3, v2, s[40:41]
	v_add_u32_e32 v2, v2, v18
	v_ashrrev_i32_e32 v3, 31, v2
	v_lshlrev_b64 v[2:3], 6, v[2:3]
	v_lshl_add_u64 v[2:3], s[28:29], 0, v[2:3]
	global_load_dword v191, v[2:3], off
.LBB0_283:
	s_or_b64 exec, exec, s[30:31]
	v_add_u32_e32 v2, 16, v13
	v_lshl_or_b32 v15, v2, 6, v1
	v_cmp_gt_i32_e64 s[46:47], s13, v2
	v_cmp_gt_i32_e32 vcc, s12, v15
	s_and_b64 s[36:37], s[46:47], vcc
	v_mov_b32_e32 v14, 0xf149f2ca
	v_mov_b32_e32 v19, 0xf149f2ca
	s_and_saveexec_b64 s[30:31], s[36:37]
	s_cbranch_execz .LBB0_285
	v_mov_b32_e32 v2, s20
	v_mov_b32_e32 v3, s21
	v_cmp_gt_i32_e32 vcc, 16, v15
	s_nop 1
	v_cndmask_b32_e32 v2, v2, v3, vcc
	v_mov_b32_e32 v3, s16
	v_cndmask_b32_e64 v2, v3, v2, s[40:41]
	v_add_u32_e32 v2, v2, v15
	v_ashrrev_i32_e32 v3, 31, v2
	v_lshlrev_b64 v[2:3], 6, v[2:3]
	v_lshl_add_u64 v[2:3], s[28:29], 0, v[2:3]
	global_load_dword v192, v[2:3], off
.LBB0_285:
	s_or_b64 exec, exec, s[30:31]
	v_add_u32_e32 v2, 24, v13
	v_lshl_or_b32 v12, v2, 6, v1
	v_cmp_gt_i32_e64 s[44:45], s13, v2
	v_cmp_gt_i32_e32 vcc, s12, v12
	s_and_b64 s[36:37], s[44:45], vcc
	s_and_saveexec_b64 s[30:31], s[36:37]
	s_cbranch_execz .LBB0_287
	v_mov_b32_e32 v2, s20
	v_mov_b32_e32 v3, s21
	v_cmp_gt_i32_e32 vcc, 16, v12
	s_nop 1
	v_cndmask_b32_e32 v2, v2, v3, vcc
	v_mov_b32_e32 v3, s16
	v_cndmask_b32_e64 v2, v3, v2, s[40:41]
	v_add_u32_e32 v2, v2, v12
	v_ashrrev_i32_e32 v3, 31, v2
	v_lshlrev_b64 v[2:3], 6, v[2:3]
	v_lshl_add_u64 v[2:3], s[28:29], 0, v[2:3]
	global_load_dword v193, v[2:3], off
.LBB0_287:
	s_or_b64 exec, exec, s[30:31]
	v_add_u32_e32 v3, 32, v13
	v_lshl_or_b32 v2, v3, 6, v1
	v_cmp_gt_i32_e32 vcc, s13, v3
	v_cmp_gt_i32_e64 s[52:53], s12, v2
	s_and_b64 s[36:37], vcc, s[52:53]
	v_mov_b32_e32 v13, 0xf149f2ca
	s_and_saveexec_b64 s[30:31], s[36:37]
	s_cbranch_execz .LBB0_289
	v_mov_b32_e32 v3, s20
	v_mov_b32_e32 v13, s21
	v_cmp_gt_i32_e64 s[52:53], 16, v2
	s_nop 1
	v_cndmask_b32_e64 v3, v3, v13, s[52:53]
	v_mov_b32_e32 v13, s16
	v_cndmask_b32_e64 v3, v13, v3, s[40:41]
	v_add_u32_e32 v22, v3, v2
	v_ashrrev_i32_e32 v23, 31, v22
	v_lshlrev_b64 v[22:23], 6, v[22:23]
	v_lshl_add_u64 v[22:23], s[28:29], 0, v[22:23]
	global_load_dword v194, v[22:23], off
.LBB0_289:
	s_or_b64 exec, exec, s[30:31]
	s_waitcnt vmcnt(0)
	v_add_f32_e32 v21, v17, v190
	v_add_f32_e32 v20, v17, v191
	v_add_f32_e32 v19, v17, v192
	v_add_f32_e32 v14, v17, v193
	v_add_f32_e32 v13, v17, v194
	v_mul_f32_e32 v3, 0x3fb8aa3b, v16
	v_exp_f32_e32 v3, v3
	s_and_saveexec_b64 s[28:29], s[50:51]
	s_cbranch_execnz .LBB0_294
	s_or_b64 exec, exec, s[28:29]
	s_and_saveexec_b64 s[28:29], s[48:49]
	s_cbranch_execnz .LBB0_299

; __device__ __forceinline__ CPar params_ptr() { CPar q = (CPar)__builtin_amdgcn_kernarg_segment_ptr(); asm volatile("" : "+s"(q)); return q; }
; __device__ __forceinline__ int lbid() { int t = blockIdx.x; asm volatile("" : "+s"(t)); return t; }
; __device__ __forceinline__ int lgdim() { int t = gridDim.x; asm volatile("" : "+s"(t)); return t; }
; __device__ __forceinline__ void phase_mixers(CPar p, int l, float* sm) {
;     ...
;     { CPar p2 = params_ptr();
;     if (wave < 4) { for (int it = lbid() * 4 + wave; it < 1024; it += lgdim() * 4) s5_item(p2, l, it >> 5, it & 31, wl); }
.LBB0_665:
	s_andn2_b64 vcc, exec, s[24:25]
	s_cbranch_vccnz .LBB0_683
	v_readlane_b32 s1, v254, 0
	s_lshl_b32 s1, s1, 2
	s_add_i32 s0, s1, s0
	s_cmpk_gt_i32 s0, 0x3ff
	s_cbranch_scc1 .LBB0_683
	v_readlane_b32 s6, v255, 42
	s_lshl_b32 s1, s6, 5
	v_readlane_b32 s7, v255, 43
	s_setprio 3
	s_branch .LBB0_669

; __device__ __forceinline__ CPar params_ptr() { CPar q = (CPar)__builtin_amdgcn_kernarg_segment_ptr(); asm volatile("" : "+s"(q)); return q; }
; __device__ __forceinline__ int ltid() { int t = threadIdx.x; asm volatile("" : "+v"(t)); return t; }
; __device__ __forceinline__ void phase_mixers(CPar p, int l, float* sm) {
;     ...
;     CPar p3 = params_ptr();
;     unsigned* ctr = (unsigned*)(p3->ws + WS_CTR) + l;
;     for (;;) {
;         unsigned it = 0; if ((ltid() & 63) == 0) it = atomicAdd(ctr, 1u);
;         it = (unsigned)__builtin_amdgcn_readfirstlane((int)it);
.LBB0_683:
	s_setprio 0
	v_readlane_b32 s18, v254, 1
	v_readlane_b32 s19, v254, 2
	s_load_dwordx2 s[0:1], s[18:19], 0x118
	v_readlane_b32 s6, v255, 42
	v_readlane_b32 s7, v255, 43
	s_mov_b32 s8, s6
	s_ashr_i32 s9, s6, 31
	s_lshl_b64 s[6:7], s[8:9], 2
	s_waitcnt lgkmcnt(0)
	s_add_u32 s6, s0, s6
	s_addc_u32 s7, s1, s7
	s_add_u32 s24, s6, 0x2600000
	s_addc_u32 s25, s7, 0
	s_add_u32 s26, s0, 0x21341000
	s_mov_b32 s0, s8
	s_addc_u32 s27, s1, 0
	v_writelane_b32 v255, s0, 42
	s_lshl_b32 s12, s8, 4
	s_lshl_b32 s13, s8, 5
	v_writelane_b32 v255, s1, 43
	s_branch .LBB0_686

; __device__ __forceinline__ unsigned pk2(float lo, float hi) { unsigned r; asm volatile("v_cvt_pk_bf16_f32 %0, %1, %2" : "=v"(r) : "v"(lo), "v"(hi)); return r; }
; __device__ __forceinline__ float lo_f(unsigned w) { return __uint_as_float(w << 16); }
; __device__ __forceinline__ float hi_f(unsigned w) { return __uint_as_float(w & 0xffff0000u); }
; __device__ __forceinline__ void attn_item(CPar p, int l, int item, float* wl) {
;     ...
;     { const u32x4* qp = (const u32x4*)(Q + (size_t)row * 512 + h * 64);
; #pragma unroll
;         for (int e = 0; e < 8; ++e) { const u32x4 w = qp[e];
; #pragma unroll
;             for (int j = 0; j < 4; ++j) q[e * 4 + j] = pk2(lo_f(w[j]) * 0.125f, hi_f(w[j]) * 0.125f); } }
.LBB0_703:
	v_add_u32_e32 v2, v3, v2
	v_ashrrev_i32_e32 v3, 31, v2
	v_lshlrev_b64 v[2:3], 10, v[2:3]
	s_lshl_b32 s28, s0, 6
	v_lshl_add_u64 v[2:3], s[26:27], 0, v[2:3]
	s_ashr_i32 s29, s28, 31
	v_lshl_add_u64 v[68:69], s[28:29], 1, v[2:3]
	global_load_dwordx4 v[80:83], v[68:69], off
	global_load_dwordx4 v[84:87], v[68:69], off offset:16
	global_load_dwordx4 v[88:91], v[68:69], off offset:32
	global_load_dwordx4 v[92:95], v[68:69], off offset:48
	global_load_dwordx4 v[96:99], v[68:69], off offset:64
	global_load_dwordx4 v[100:103], v[68:69], off offset:80
	global_load_dwordx4 v[104:107], v[68:69], off offset:96
	global_load_dwordx4 v[108:111], v[68:69], off offset:112
	s_and_b64 vcc, exec, s[30:31]
	s_waitcnt vmcnt(0)
	v_mov_b32_e32 v2, v80
	v_mov_b32_e32 v3, v81
	v_mov_b32_e32 v4, v82
	v_mov_b32_e32 v5, v83
	v_lshlrev_b32_e32 v6, 16, v2
	v_and_b32_e32 v2, 0xffff0000, v2
	v_mul_f32_e32 v2, 0x3e000000, v2
	v_mul_f32_e32 v6, 0x3e000000, v6
	v_cvt_pk_bf16_f32 v80, v6, v2
	v_lshlrev_b32_e32 v2, 16, v3
	v_and_b32_e32 v3, 0xffff0000, v3
	v_mul_f32_e32 v2, 0x3e000000, v2
	v_mul_f32_e32 v3, 0x3e000000, v3
	v_cvt_pk_bf16_f32 v81, v2, v3
	v_lshlrev_b32_e32 v2, 16, v4
	v_and_b32_e32 v3, 0xffff0000, v4
	v_mul_f32_e32 v2, 0x3e000000, v2
	v_mul_f32_e32 v3, 0x3e000000, v3
	v_cvt_pk_bf16_f32 v82, v2, v3
	v_lshlrev_b32_e32 v2, 16, v5
	v_and_b32_e32 v3, 0xffff0000, v5
	v_mul_f32_e32 v2, 0x3e000000, v2
	v_mul_f32_e32 v3, 0x3e000000, v3
	v_cvt_pk_bf16_f32 v83, v2, v3
	v_mov_b32_e32 v2, v84
	v_mov_b32_e32 v3, v85
	v_mov_b32_e32 v4, v86
	v_mov_b32_e32 v5, v87
	v_lshlrev_b32_e32 v6, 16, v2
	v_and_b32_e32 v2, 0xffff0000, v2
	v_mul_f32_e32 v2, 0x3e000000, v2
	v_mul_f32_e32 v6, 0x3e000000, v6
	v_cvt_pk_bf16_f32 v84, v6, v2
	v_lshlrev_b32_e32 v2, 16, v3
	v_and_b32_e32 v3, 0xffff0000, v3
	v_mul_f32_e32 v2, 0x3e000000, v2
	v_mul_f32_e32 v3, 0x3e000000, v3
	v_cvt_pk_bf16_f32 v85, v2, v3
	v_lshlrev_b32_e32 v2, 16, v4
	v_and_b32_e32 v3, 0xffff0000, v4
	v_mul_f32_e32 v2, 0x3e000000, v2
	v_mul_f32_e32 v3, 0x3e000000, v3
	v_cvt_pk_bf16_f32 v86, v2, v3
	v_lshlrev_b32_e32 v2, 16, v5
	v_and_b32_e32 v3, 0xffff0000, v5
	v_mul_f32_e32 v2, 0x3e000000, v2
	v_mul_f32_e32 v3, 0x3e000000, v3
	v_cvt_pk_bf16_f32 v87, v2, v3
	v_mov_b32_e32 v2, v88
	v_mov_b32_e32 v3, v89
	v_mov_b32_e32 v4, v90
	v_mov_b32_e32 v5, v91
	v_lshlrev_b32_e32 v6, 16, v2
	v_and_b32_e32 v2, 0xffff0000, v2
	v_mul_f32_e32 v2, 0x3e000000, v2
	v_mul_f32_e32 v6, 0x3e000000, v6
	v_cvt_pk_bf16_f32 v88, v6, v2
	v_lshlrev_b32_e32 v2, 16, v3
	v_and_b32_e32 v3, 0xffff0000, v3
	v_mul_f32_e32 v2, 0x3e000000, v2
	v_mul_f32_e32 v3, 0x3e000000, v3
	v_cvt_pk_bf16_f32 v89, v2, v3
	v_lshlrev_b32_e32 v2, 16, v4
	v_and_b32_e32 v3, 0xffff0000, v4
	v_mul_f32_e32 v2, 0x3e000000, v2
	v_mul_f32_e32 v3, 0x3e000000, v3
	v_cvt_pk_bf16_f32 v90, v2, v3
	v_lshlrev_b32_e32 v2, 16, v5
	v_and_b32_e32 v3, 0xffff0000, v5
	v_mul_f32_e32 v2, 0x3e000000, v2
	v_mul_f32_e32 v3, 0x3e000000, v3
	v_cvt_pk_bf16_f32 v91, v2, v3
	v_mov_b32_e32 v2, v92
	v_mov_b32_e32 v3, v93
	v_mov_b32_e32 v4, v94
	v_mov_b32_e32 v5, v95
	v_lshlrev_b32_e32 v6, 16, v2
	v_and_b32_e32 v2, 0xffff0000, v2
	v_mul_f32_e32 v2, 0x3e000000, v2
	v_mul_f32_e32 v6, 0x3e000000, v6
	v_cvt_pk_bf16_f32 v92, v6, v2
	v_lshlrev_b32_e32 v2, 16, v3
	v_and_b32_e32 v3, 0xffff0000, v3
	v_mul_f32_e32 v2, 0x3e000000, v2
	v_mul_f32_e32 v3, 0x3e000000, v3
	v_cvt_pk_bf16_f32 v93, v2, v3
	v_lshlrev_b32_e32 v2, 16, v4
	v_and_b32_e32 v3, 0xffff0000, v4
	v_mul_f32_e32 v2, 0x3e000000, v2
	v_mul_f32_e32 v3, 0x3e000000, v3
	v_cvt_pk_bf16_f32 v94, v2, v3
	v_lshlrev_b32_e32 v2, 16, v5
	v_and_b32_e32 v3, 0xffff0000, v5
	v_mul_f32_e32 v2, 0x3e000000, v2
	v_mul_f32_e32 v3, 0x3e000000, v3
	v_cvt_pk_bf16_f32 v95, v2, v3
	v_mov_b32_e32 v2, v96
	v_mov_b32_e32 v3, v97
	v_mov_b32_e32 v4, v98
	v_mov_b32_e32 v5, v99
	v_lshlrev_b32_e32 v6, 16, v2
	v_and_b32_e32 v2, 0xffff0000, v2
	v_mul_f32_e32 v2, 0x3e000000, v2
	v_mul_f32_e32 v6, 0x3e000000, v6
	v_cvt_pk_bf16_f32 v96, v6, v2
	v_lshlrev_b32_e32 v2, 16, v3
; __device__ __forceinline__ unsigned pk2(float lo, float hi) { unsigned r; asm volatile("v_cvt_pk_bf16_f32 %0, %1, %2" : "=v"(r) : "v"(lo), "v"(hi)); return r; }
; __device__ __forceinline__ float lo_f(unsigned w) { return __uint_as_float(w << 16); }
; __device__ __forceinline__ float hi_f(unsigned w) { return __uint_as_float(w & 0xffff0000u); }
; __device__ __forceinline__ void attn_item(CPar p, int l, int item, float* wl) {
;     ...
;     { const u32x4* qp = (const u32x4*)(Q + (size_t)row * 512 + h * 64);
; #pragma unroll
;         for (int e = 0; e < 8; ++e) { const u32x4 w = qp[e];
; #pragma unroll
;             for (int j = 0; j < 4; ++j) q[e * 4 + j] = pk2(lo_f(w[j]) * 0.125f, hi_f(w[j]) * 0.125f); } }
	v_and_b32_e32 v3, 0xffff0000, v3
	v_mul_f32_e32 v2, 0x3e000000, v2
	v_mul_f32_e32 v3, 0x3e000000, v3
	v_cvt_pk_bf16_f32 v97, v2, v3
	v_lshlrev_b32_e32 v2, 16, v4
	v_and_b32_e32 v3, 0xffff0000, v4
	v_mul_f32_e32 v2, 0x3e000000, v2
	v_mul_f32_e32 v3, 0x3e000000, v3
	v_cvt_pk_bf16_f32 v98, v2, v3
	v_lshlrev_b32_e32 v2, 16, v5
	v_and_b32_e32 v3, 0xffff0000, v5
	v_mul_f32_e32 v2, 0x3e000000, v2
	v_mul_f32_e32 v3, 0x3e000000, v3
	v_cvt_pk_bf16_f32 v99, v2, v3
	v_mov_b32_e32 v2, v100
	v_mov_b32_e32 v3, v101
	v_mov_b32_e32 v4, v102
	v_mov_b32_e32 v5, v103
	v_lshlrev_b32_e32 v6, 16, v2
	v_and_b32_e32 v2, 0xffff0000, v2
	v_mul_f32_e32 v2, 0x3e000000, v2
	v_mul_f32_e32 v6, 0x3e000000, v6
	v_cvt_pk_bf16_f32 v100, v6, v2
	v_lshlrev_b32_e32 v2, 16, v3
	v_and_b32_e32 v3, 0xffff0000, v3
	v_mul_f32_e32 v2, 0x3e000000, v2
	v_mul_f32_e32 v3, 0x3e000000, v3
	v_cvt_pk_bf16_f32 v101, v2, v3
	v_lshlrev_b32_e32 v2, 16, v4
	v_and_b32_e32 v3, 0xffff0000, v4
	v_mul_f32_e32 v2, 0x3e000000, v2
	v_mul_f32_e32 v3, 0x3e000000, v3
	v_cvt_pk_bf16_f32 v102, v2, v3
	v_lshlrev_b32_e32 v2, 16, v5
	v_and_b32_e32 v3, 0xffff0000, v5
	v_mul_f32_e32 v2, 0x3e000000, v2
	v_mul_f32_e32 v3, 0x3e000000, v3
	v_cvt_pk_bf16_f32 v103, v2, v3
	v_mov_b32_e32 v2, v104
	v_mov_b32_e32 v3, v105
	v_mov_b32_e32 v4, v106
	v_mov_b32_e32 v5, v107
	v_lshlrev_b32_e32 v6, 16, v2
	v_and_b32_e32 v2, 0xffff0000, v2
	v_mul_f32_e32 v2, 0x3e000000, v2
	v_mul_f32_e32 v6, 0x3e000000, v6
	v_cvt_pk_bf16_f32 v104, v6, v2
	v_lshlrev_b32_e32 v2, 16, v3
	v_and_b32_e32 v3, 0xffff0000, v3
	v_mul_f32_e32 v2, 0x3e000000, v2
	v_mul_f32_e32 v3, 0x3e000000, v3
	v_cvt_pk_bf16_f32 v105, v2, v3
	v_lshlrev_b32_e32 v2, 16, v4
	v_and_b32_e32 v3, 0xffff0000, v4
	v_mul_f32_e32 v2, 0x3e000000, v2
	v_mul_f32_e32 v3, 0x3e000000, v3
	v_cvt_pk_bf16_f32 v106, v2, v3
	v_lshlrev_b32_e32 v2, 16, v5
	v_and_b32_e32 v3, 0xffff0000, v5
	v_mul_f32_e32 v2, 0x3e000000, v2
	v_mul_f32_e32 v3, 0x3e000000, v3
	v_cvt_pk_bf16_f32 v107, v2, v3
	v_mov_b32_e32 v2, v108
	v_mov_b32_e32 v3, v109
	v_mov_b32_e32 v4, v110
	v_mov_b32_e32 v5, v111
	v_lshlrev_b32_e32 v6, 16, v2
	v_and_b32_e32 v2, 0xffff0000, v2
	v_mul_f32_e32 v2, 0x3e000000, v2
	v_mul_f32_e32 v6, 0x3e000000, v6
	v_cvt_pk_bf16_f32 v108, v6, v2
	v_lshlrev_b32_e32 v2, 16, v3
	v_and_b32_e32 v3, 0xffff0000, v3
	v_mul_f32_e32 v2, 0x3e000000, v2
	v_mul_f32_e32 v3, 0x3e000000, v3
	v_cvt_pk_bf16_f32 v109, v2, v3
	v_lshlrev_b32_e32 v2, 16, v4
	v_and_b32_e32 v3, 0xffff0000, v4
	v_mul_f32_e32 v2, 0x3e000000, v2
	v_mul_f32_e32 v3, 0x3e000000, v3
	v_cvt_pk_bf16_f32 v110, v2, v3
	v_lshlrev_b32_e32 v2, 16, v5
	v_and_b32_e32 v3, 0xffff0000, v5
	v_mul_f32_e32 v2, 0x3e000000, v2
	v_mul_f32_e32 v3, 0x3e000000, v3
	v_cvt_pk_bf16_f32 v111, v2, v3
	v_mbcnt_lo_u32_b32 v2, -1, 0
	v_mbcnt_hi_u32_b32 v2, -1, v2
	v_mul_u32_u24_e32 v3, 0x90, v2
	v_add_u32_e32 v3, s52, v3
	ds_write_b128 v3, v[80:83]
	ds_write_b128 v3, v[84:87] offset:16
	ds_write_b128 v3, v[88:91] offset:32
	ds_write_b128 v3, v[92:95] offset:48
	ds_write_b128 v3, v[96:99] offset:64
	ds_write_b128 v3, v[100:103] offset:80
	ds_write_b128 v3, v[104:107] offset:96
	ds_write_b128 v3, v[108:111] offset:112
	v_and_b32_e32 v4, 15, v2
	v_lshrrev_b32_e32 v5, 4, v2
	v_mul_u32_u24_e32 v4, 0x90, v4
	v_lshl_add_u32 v4, v5, 4, v4
	v_add_u32_e32 v4, s52, v4
	s_waitcnt lgkmcnt(0)
	ds_read_b128 v[80:83], v4
	ds_read_b128 v[84:87], v4 offset:64
	ds_read_b128 v[88:91], v4 offset:2304
	ds_read_b128 v[92:95], v4 offset:2368
	ds_read_b128 v[96:99], v4 offset:4608
	ds_read_b128 v[100:103], v4 offset:4672
	ds_read_b128 v[104:107], v4 offset:6912
	ds_read_b128 v[108:111], v4 offset:6976
	s_waitcnt lgkmcnt(0)
	s_load_dwordx2 s[34:35], s[18:19], 0x110
	v_add_u32_e32 v4, s12, v1
	v_ashrrev_i32_e32 v5, 31, v4
	s_cbranch_vccz .LBB0_705
	v_lshlrev_b64 v[2:3], 17, v[4:5]
	s_waitcnt lgkmcnt(0)
	v_lshl_add_u64 v[2:3], s[34:35], 0, v[2:3]
	s_mov_b64 s[6:7], 0x319f0000
	v_lshl_add_u64 v[2:3], v[2:3], 0, s[6:7]
	s_cbranch_execz .LBB0_706
	s_branch .LBB0_707

; __device__ __forceinline__ float dot2bf(unsigned a, unsigned b, float c) { return __builtin_amdgcn_fdot2_f32_bf16(__builtin_bit_cast(bf2_t, a), __builtin_bit_cast(bf2_t, b), c, false); }
; __device__ __forceinline__ void attn_item(CPar p, int l, int item, float* wl) {
;     ...
;         const int nk = jt + 1 < 32 ? jt + 1 : 32, npair = (nk + 1) >> 1;
;         for (int m = 0; m < npair; ++m) { const int j0 = jt - 2 * m, j1 = j0 - 1;
;             float z0 = 0.f, z1 = 0.f;
; #pragma unroll
;             for (int d8 = 0; d8 < 8; ++d8) { const u32x4 k0 = *(const u32x4*)(Kt + (2 * m) * 32 + d8 * 4), k1 = *(const u32x4*)(Kt + (2 * m + 1) * 32 + d8 * 4);
; #pragma unroll
;                 for (int c = 0; c < 4; ++c) { z0 = dot2bf(q[d8 * 4 + c], k0[c], z0); z1 = dot2bf(q[d8 * 4 + c], k1[c], z1); } }
.LBB0_770:
	s_min_i32 s6, s1, 31
	s_add_i32 s6, s6, 2
	s_lshr_b32 s6, s6, 1
	s_max_u32 s6, s6, 1
	s_sub_i32 s6, 0, s6
	v_mov_b32_e32 v1, s6
	s_mov_b32 s9, s52
	v_mbcnt_lo_u32_b32 v250, -1, 0
	v_mbcnt_hi_u32_b32 v250, -1, v250
	v_and_b32_e32 v251, 15, v250
	v_lshrrev_b32_e32 v252, 4, v250
	v_lshlrev_b32_e32 v253, 7, v251
	v_lshl_add_u32 v253, v252, 4, v253
	v_add_u32_e32 v253, s52, v253
	v_mul_u32_u24_e32 v251, 0x90, v251
	v_lshl_add_u32 v251, v252, 4, v251
	v_add_u32_e32 v251, s52, v251
	v_add_u32_e32 v251, 0x2000, v251
	ds_read_b128 v[242:245], v253
	ds_read_b128 v[246:249], v253 offset:64
	s_waitcnt lgkmcnt(0)
	v_mfma_f32_16x16x32_bf16 v[226:229], v[242:245], v[80:83], 0
	v_mfma_f32_16x16x32_bf16 v[230:233], v[242:245], v[88:91], 0
	v_mfma_f32_16x16x32_bf16 v[234:237], v[242:245], v[96:99], 0
	v_mfma_f32_16x16x32_bf16 v[238:241], v[242:245], v[104:107], 0
	v_mfma_f32_16x16x32_bf16 v[226:229], v[246:249], v[84:87], v[226:229]
	v_mfma_f32_16x16x32_bf16 v[230:233], v[246:249], v[92:95], v[230:233]
	v_mfma_f32_16x16x32_bf16 v[234:237], v[246:249], v[100:103], v[234:237]
	v_mfma_f32_16x16x32_bf16 v[238:241], v[246:249], v[108:111], v[238:241]
	s_nop 7
	s_nop 1
	ds_write_b128 v251, v[226:229]
	ds_write_b128 v251, v[230:233] offset:2304
	ds_write_b128 v251, v[234:237] offset:4608
	ds_write_b128 v251, v[238:241] offset:6912
	ds_read_b128 v[242:245], v253 offset:2048
	ds_read_b128 v[246:249], v253 offset:2112
	s_waitcnt lgkmcnt(0)
	v_mfma_f32_16x16x32_bf16 v[226:229], v[242:245], v[80:83], 0
	v_mfma_f32_16x16x32_bf16 v[230:233], v[242:245], v[88:91], 0
	v_mfma_f32_16x16x32_bf16 v[234:237], v[242:245], v[96:99], 0
	v_mfma_f32_16x16x32_bf16 v[238:241], v[242:245], v[104:107], 0
	v_mfma_f32_16x16x32_bf16 v[226:229], v[246:249], v[84:87], v[226:229]
	v_mfma_f32_16x16x32_bf16 v[230:233], v[246:249], v[92:95], v[230:233]
	v_mfma_f32_16x16x32_bf16 v[234:237], v[246:249], v[100:103], v[234:237]
	v_mfma_f32_16x16x32_bf16 v[238:241], v[246:249], v[108:111], v[238:241]
	s_nop 7
	s_nop 1
	ds_write_b128 v251, v[226:229] offset:64
	ds_write_b128 v251, v[230:233] offset:2368
	ds_write_b128 v251, v[234:237] offset:4672
	ds_write_b128 v251, v[238:241] offset:6976
	s_waitcnt lgkmcnt(0)
	v_mul_u32_u24_e32 v250, 0x90, v250
	v_add_u32_e32 v250, s52, v250
	v_add_u32_e32 v250, 0x2000, v250
; __device__ __forceinline__ unsigned pk2(float lo, float hi) { unsigned r; asm volatile("v_cvt_pk_bf16_f32 %0, %1, %2" : "=v"(r) : "v"(lo), "v"(hi)); return r; }
; __device__ __forceinline__ float dot2bf(unsigned a, unsigned b, float c) { return __builtin_amdgcn_fdot2_f32_bf16(__builtin_bit_cast(bf2_t, a), __builtin_bit_cast(bf2_t, b), c, false); }
; __device__ __forceinline__ void attn_item(CPar p, int l, int item, float* wl) {
;     ...
;         for (int m = 0; m < npair; ++m) { const int j0 = jt - 2 * m, j1 = j0 - 1;
;             float z0 = 0.f, z1 = 0.f;
; #pragma unroll
;             for (int d8 = 0; d8 < 8; ++d8) { const u32x4 k0 = *(const u32x4*)(Kt + (2 * m) * 32 + d8 * 4), k1 = *(const u32x4*)(Kt + (2 * m + 1) * 32 + d8 * 4);
; #pragma unroll
;                 for (int c = 0; c < 4; ++c) { z0 = dot2bf(q[d8 * 4 + c], k0[c], z0); z1 = dot2bf(q[d8 * 4 + c], k1[c], z1); } }
;             const bool v0 = active && (j0 < nh + i), v1 = active && (j1 >= 0) && (j1 < nh + i);
;             const float e0 = __expf(-z0), ls0 = -__logf(1.f + e0);
;             const float w0 = v0 ? __expf(ls0 + run) : 0.f; run += v0 ? (ls0 - z0) : 0.f;
;             const float e1 = __expf(-z1), ls1 = -__logf(1.f + e1);
;             const float w1 = v1 ? __expf(ls1 + run) : 0.f; run += v1 ? (ls1 - z1) : 0.f;
;             const unsigned wp = pk2(w0, w1);
; #pragma unroll
;             for (int d4 = 0; d4 < 16; ++d4) { const u32x4 vv = *(const u32x4*)(Vp + m * 64 + d4 * 4);
; #pragma unroll
;                 for (int c = 0; c < 4; ++c) o[d4 * 4 + c] = dot2bf(wp, vv[c], o[d4 * 4 + c]); } }
.LBB0_771:
	v_mov_b32_e32 v2, s9
	ds_read_b64 v[252:253], v250
	ds_read_b128 v[226:229], v2 offset:4096
	ds_read_b128 v[230:233], v2 offset:4112
	ds_read_b128 v[234:237], v2 offset:4128
	ds_read_b128 v[238:241], v2 offset:4144
	ds_read_b128 v[242:245], v2 offset:4160
	ds_read_b128 v[246:249], v2 offset:4176
	v_add_u32_e32 v250, 8, v250
	v_cmp_lt_i32_e32 vcc, s1, v184
	s_and_b64 vcc, s[40:41], vcc
	s_cmp_gt_i32 s1, 0
	s_cselect_b64 s[6:7], -1, 0
	s_and_b64 s[6:7], s[40:41], s[6:7]
	v_cmp_le_i32_e64 s[44:45], s1, v184
	s_addk_i32 s9, 0x100
	s_add_i32 s1, s1, -2
	s_waitcnt lgkmcnt(6)
	v_mov_b32_e32 v3, v252
	v_mov_b32_e32 v79, v253
	s_and_b64 s[44:45], s[6:7], s[44:45]
	v_mul_f32_e32 v212, 0xbfb8aa3b, v3
	v_exp_f32_e32 v212, v212
	s_nop 0
	v_add_f32_e32 v212, 1.0, v212
	v_cmp_gt_f32_e64 s[46:47], s38, v212
	s_nop 1
	v_cndmask_b32_e64 v213, 0, 32, s[46:47]
	v_ldexp_f32 v212, v212, v213
	v_log_f32_e32 v212, v212
	s_nop 0
	v_mul_f32_e32 v213, 0x3f317217, v212
	v_fma_f32 v213, v212, s90, -v213
	v_fmac_f32_e32 v213, 0x3377d1cf, v212
	v_fmac_f32_e32 v213, 0x3f317217, v212
	v_cmp_lt_f32_e64 s[48:49], |v212|, s23
	s_nop 1
	v_cndmask_b32_e64 v212, v212, v213, s[48:49]
	v_cndmask_b32_e64 v213, 0, v211, s[46:47]
	v_sub_f32_e32 v212, v212, v213
	v_sub_f32_e32 v213, v224, v212
	v_sub_f32_e64 v3, -v212, v3
	v_mul_f32_e32 v212, 0xbfb8aa3b, v79
	v_mul_f32_e32 v213, 0x3fb8aa3b, v213
	v_exp_f32_e32 v212, v212
	v_exp_f32_e32 v213, v213
	v_cndmask_b32_e32 v3, 0, v3, vcc
	v_add_f32_e32 v3, v224, v3
	v_add_f32_e32 v212, 1.0, v212
	v_cndmask_b32_e32 v213, 0, v213, vcc
	v_cmp_gt_f32_e32 vcc, s38, v212
	s_nop 1
	v_cndmask_b32_e64 v224, 0, 32, vcc
	v_ldexp_f32 v212, v212, v224
	v_log_f32_e32 v212, v212
	s_nop 0
	v_mul_f32_e32 v224, 0x3f317217, v212
	v_fma_f32 v224, v212, s90, -v224
	v_fmac_f32_e32 v224, 0x3377d1cf, v212
	v_fmac_f32_e32 v224, 0x3f317217, v212
	v_cmp_lt_f32_e64 s[46:47], |v212|, s23
	s_nop 1
	v_cndmask_b32_e64 v212, v212, v224, s[46:47]
	v_cndmask_b32_e32 v224, 0, v211, vcc
	v_sub_f32_e32 v212, v212, v224
	v_sub_f32_e32 v224, v3, v212
	v_mul_f32_e32 v224, 0x3fb8aa3b, v224
	v_exp_f32_e32 v224, v224
	v_sub_f32_e64 v79, -v212, v79
	v_cndmask_b32_e64 v79, 0, v79, s[44:45]
	v_add_co_u32_e32 v1, vcc, 1, v1
	v_cndmask_b32_e64 v224, 0, v224, s[44:45]
	v_cvt_pk_bf16_f32 v212, v213, v224
	s_and_b64 vcc, exec, vcc
	s_waitcnt lgkmcnt(5)
	v_dot2c_f32_bf16_e32 v223, v212, v226
	v_dot2c_f32_bf16_e32 v222, v212, v227
	v_dot2c_f32_bf16_e32 v221, v212, v228
	v_dot2c_f32_bf16_e32 v220, v212, v229
	ds_read_b128 v[226:229], v2 offset:4192
	s_waitcnt lgkmcnt(5)
	v_dot2c_f32_bf16_e32 v219, v212, v230
	v_dot2c_f32_bf16_e32 v218, v212, v231
	v_dot2c_f32_bf16_e32 v217, v212, v232
	v_dot2c_f32_bf16_e32 v216, v212, v233
	ds_read_b128 v[230:233], v2 offset:4208
	s_waitcnt lgkmcnt(5)
	v_dot2c_f32_bf16_e32 v199, v212, v234
	v_dot2c_f32_bf16_e32 v198, v212, v235
	v_dot2c_f32_bf16_e32 v197, v212, v236
	v_dot2c_f32_bf16_e32 v196, v212, v237
	ds_read_b128 v[234:237], v2 offset:4224
	s_waitcnt lgkmcnt(5)
	v_dot2c_f32_bf16_e32 v195, v212, v238
	v_dot2c_f32_bf16_e32 v194, v212, v239
	v_dot2c_f32_bf16_e32 v193, v212, v240
	v_dot2c_f32_bf16_e32 v192, v212, v241
	ds_read_b128 v[238:241], v2 offset:4240
	s_waitcnt lgkmcnt(5)
	v_dot2c_f32_bf16_e32 v191, v212, v242
	v_dot2c_f32_bf16_e32 v190, v212, v243
	v_dot2c_f32_bf16_e32 v188, v212, v244
	v_dot2c_f32_bf16_e32 v187, v212, v245
	ds_read_b128 v[242:245], v2 offset:4256
	s_waitcnt lgkmcnt(5)
	v_dot2c_f32_bf16_e32 v185, v212, v246
	v_dot2c_f32_bf16_e32 v183, v212, v247
	v_dot2c_f32_bf16_e32 v182, v212, v248
	v_dot2c_f32_bf16_e32 v181, v212, v249
	ds_read_b128 v[246:249], v2 offset:4272
	s_waitcnt lgkmcnt(5)
	v_dot2c_f32_bf16_e32 v180, v212, v226
	v_dot2c_f32_bf16_e32 v179, v212, v227
	v_dot2c_f32_bf16_e32 v178, v212, v228
	v_dot2c_f32_bf16_e32 v177, v212, v229
	ds_read_b128 v[226:229], v2 offset:4288
	s_waitcnt lgkmcnt(5)
	v_dot2c_f32_bf16_e32 v176, v212, v230
	v_dot2c_f32_bf16_e32 v171, v212, v231
	v_dot2c_f32_bf16_e32 v158, v212, v232
	v_dot2c_f32_bf16_e32 v157, v212, v233
	ds_read_b128 v[230:233], v2 offset:4304
	s_waitcnt lgkmcnt(5)
	v_dot2c_f32_bf16_e32 v155, v212, v234
	v_dot2c_f32_bf16_e32 v154, v212, v235
	v_dot2c_f32_bf16_e32 v153, v212, v236
	v_dot2c_f32_bf16_e32 v152, v212, v237
	ds_read_b128 v[234:237], v2 offset:4320
	s_waitcnt lgkmcnt(5)
	v_dot2c_f32_bf16_e32 v151, v212, v238
	v_dot2c_f32_bf16_e32 v150, v212, v239
	v_dot2c_f32_bf16_e32 v149, v212, v240
	v_dot2c_f32_bf16_e32 v148, v212, v241
	ds_read_b128 v[238:241], v2 offset:4336
	s_waitcnt lgkmcnt(5)
	v_dot2c_f32_bf16_e32 v147, v212, v242
	v_dot2c_f32_bf16_e32 v146, v212, v243
	v_dot2c_f32_bf16_e32 v145, v212, v244
	v_dot2c_f32_bf16_e32 v144, v212, v245
	s_waitcnt lgkmcnt(4)
	v_dot2c_f32_bf16_e32 v143, v212, v246
	v_dot2c_f32_bf16_e32 v142, v212, v247
	v_dot2c_f32_bf16_e32 v141, v212, v248
	v_dot2c_f32_bf16_e32 v140, v212, v249
	s_waitcnt lgkmcnt(3)
	v_dot2c_f32_bf16_e32 v139, v212, v226
	v_dot2c_f32_bf16_e32 v138, v212, v227
	v_dot2c_f32_bf16_e32 v137, v212, v228
	v_dot2c_f32_bf16_e32 v136, v212, v229
	s_waitcnt lgkmcnt(2)
	v_dot2c_f32_bf16_e32 v135, v212, v230
	v_dot2c_f32_bf16_e32 v134, v212, v231
	v_dot2c_f32_bf16_e32 v133, v212, v232
	v_dot2c_f32_bf16_e32 v132, v212, v233
	s_waitcnt lgkmcnt(1)
	v_dot2c_f32_bf16_e32 v131, v212, v234
	v_dot2c_f32_bf16_e32 v130, v212, v235
	v_dot2c_f32_bf16_e32 v129, v212, v236
	v_dot2c_f32_bf16_e32 v128, v212, v237
	s_waitcnt lgkmcnt(0)
	v_dot2c_f32_bf16_e32 v127, v212, v238
	v_dot2c_f32_bf16_e32 v126, v212, v239
	v_dot2c_f32_bf16_e32 v125, v212, v240
	v_dot2c_f32_bf16_e32 v124, v212, v241
	v_add_f32_e32 v224, v3, v79
	s_cbranch_vccz .LBB0_771
	s_mov_b32 s1, 0xc2480000
	v_cmp_gt_f32_e32 vcc, s1, v224
	s_or_b64 s[6:7], s[42:43], vcc
	s_waitcnt lgkmcnt(0)
	v_cndmask_b32_e64 v1, 0, 1, s[6:7]
	v_cmp_ne_u32_e32 vcc, 0, v1
	s_cmp_eq_u64 vcc, exec
	s_cselect_b64 s[28:29], -1, 0
	s_and_b64 vcc, exec, s[28:29]
	s_cbranch_vccz .LBB0_774
	s_branch .LBB0_775
